# E67: E66 minus the redundant leading vmcnt(3) ahead of the counted staging-write waits in the diff loop's first tile copy
# baseline (speedup 1.0000x reference)
; #define SBAR() __builtin_amdgcn_sched_barrier(0)
; template <int D0> __device__ __forceinline__ void pv_one_mi(f32x16& od, int vb, bf16x8 pa0, bf16x8 pa1, bf16x8 pa2, bf16x8 pa3, f32x16& q0) {
;   const s16x4 l0 = tr_read<v_rd_off(D0, 0, 0)>(vb), h0 = tr_read<v_rd_off(D0, 0, 1)>(vb), l1 = tr_read<v_rd_off(D0, 1, 0)>(vb), h1 = tr_read<v_rd_off(D0, 1, 1)>(vb);
;   const s16x4 l2 = tr_read<v_rd_off(D0, 2, 0)>(vb), h2 = tr_read<v_rd_off(D0, 2, 1)>(vb), l3 = tr_read<v_rd_off(D0, 3, 0)>(vb), h3 = tr_read<v_rd_off(D0, 3, 1)>(vb);
;   asm volatile("s_waitcnt lgkmcnt(0)" ::: "memory"); SBAR();
;     ...
;   od = __builtin_amdgcn_mfma_f32_32x32x16_bf16(pa0, PK(l0, h0), od, 0, 0, 0);
;   od = __builtin_amdgcn_mfma_f32_32x32x16_bf16(pa1, PK(l1, h1), od, 0, 0, 0);
;   od = __builtin_amdgcn_mfma_f32_32x32x16_bf16(pa2, PK(l2, h2), od, 0, 0, 0);
;   od = __builtin_amdgcn_mfma_f32_32x32x16_bf16(pa3, PK(l3, h3), od, 0, 0, 0);
;     ...
; #pragma unroll
;   for (int r = 4 * D0; r < 4 * D0 + 4; ++r) q0[r] = __builtin_amdgcn_exp2f(q0[r]);
; }
; __device__ __forceinline__ void pv_mi(f32x16* o, int vb, bf16x8 pa0, bf16x8 pa1, bf16x8 pa2, bf16x8 pa3, f32x16& q0) {
;   pv_one_mi<0>(o[0], vb, pa0, pa1, pa2, pa3, q0); pv_one_mi<1>(o[1], vb, pa0, pa1, pa2, pa3, q0);
;   pv_one_mi<2>(o[2], vb, pa0, pa1, pa2, pa3, q0); pv_one_mi<3>(o[3], vb, pa0, pa1, pa2, pa3, q0);
; }
.LBB0_1288:
	v_cvt_pk_bf16_f32 v232, v175, v176
	v_cvt_pk_bf16_f32 v233, v177, v178
	v_cvt_pk_bf16_f32 v234, v179, v181
	v_cvt_pk_bf16_f32 v235, v183, v185
	v_cvt_pk_bf16_f32 v236, v180, v182
	v_cvt_pk_bf16_f32 v237, v184, v227
	v_cvt_pk_bf16_f32 v238, v228, v229
	v_cvt_pk_bf16_f32 v239, v230, v174
	v_cvt_pk_bf16_f32 v228, v96, v97
	v_cvt_pk_bf16_f32 v229, v215, v99
	v_cvt_pk_bf16_f32 v230, v100, v101
	v_cvt_pk_bf16_f32 v231, v102, v103
	v_cvt_pk_bf16_f32 v96, v98, v104
	v_cvt_pk_bf16_f32 v97, v105, v106
	v_cvt_pk_bf16_f32 v98, v107, v108
	v_cvt_pk_bf16_f32 v99, v109, v110
	s_add_i32 s8, s13, 0xfffe8000
	s_add_i32 s9, s12, 0xfffe0000
	s_mov_b32 s38, s30
	s_mov_b32 s39, s31
	s_add_i32 s10, s13, 0xffff0000
	buffer_load_dwordx4 v[174:177], v216, s[28:31], s8 offen
	buffer_load_dwordx4 v[178:181], v216, s[28:31], s10 offen
	buffer_load_dwordx4 v[182:185], v217, s[36:39], s9 offen
	s_lshl_b32 s10, s58, 14
	v_add_u32_e32 v215, s10, v214
	ds_read_b64_tr_b16 v[100:101], v215 offset:0
	ds_read_b64_tr_b16 v[102:103], v215 offset:0x800
	ds_read_b64_tr_b16 v[104:105], v215 offset:0x1000
	ds_read_b64_tr_b16 v[106:107], v215 offset:0x1800
	ds_read_b64_tr_b16 v[108:109], v215 offset:0x2000
	ds_read_b64_tr_b16 v[110:111], v215 offset:0x2800
	ds_read_b64_tr_b16 v[240:241], v215 offset:0x3000
	ds_read_b64_tr_b16 v[242:243], v215 offset:0x3800
	s_waitcnt lgkmcnt(6)
	s_nop 0
	v_mfma_f32_32x32x16_bf16 v[0:15], v[232:235], v[100:103], v[0:15]
	ds_read_b64_tr_b16 v[100:101], v215 offset:0x200
	ds_read_b64_tr_b16 v[102:103], v215 offset:0xa00
	s_waitcnt lgkmcnt(6)
	v_mfma_f32_32x32x16_bf16 v[0:15], v[236:239], v[104:107], v[0:15]
	ds_read_b64_tr_b16 v[104:105], v215 offset:0x1200
	ds_read_b64_tr_b16 v[106:107], v215 offset:0x1a00
	s_waitcnt lgkmcnt(6)
	v_mfma_f32_32x32x16_bf16 v[0:15], v[228:231], v[108:111], v[0:15]
	ds_read_b64_tr_b16 v[108:109], v215 offset:0x2200
	ds_read_b64_tr_b16 v[110:111], v215 offset:0x2a00
	s_waitcnt lgkmcnt(6)
	v_mfma_f32_32x32x16_bf16 v[0:15], v[96:99], v[240:243], v[0:15]
	ds_read_b64_tr_b16 v[240:241], v215 offset:0x3200
	ds_read_b64_tr_b16 v[242:243], v215 offset:0x3a00
	s_waitcnt lgkmcnt(6)
	v_mfma_f32_32x32x16_bf16 v[48:63], v[232:235], v[100:103], v[48:63]
	ds_read_b64_tr_b16 v[100:101], v215 offset:0x400
	ds_read_b64_tr_b16 v[102:103], v215 offset:0xc00
	s_waitcnt lgkmcnt(6)
	v_mfma_f32_32x32x16_bf16 v[48:63], v[236:239], v[104:107], v[48:63]
	ds_read_b64_tr_b16 v[104:105], v215 offset:0x1400
	ds_read_b64_tr_b16 v[106:107], v215 offset:0x1c00
	s_waitcnt lgkmcnt(6)
	v_mfma_f32_32x32x16_bf16 v[48:63], v[228:231], v[108:111], v[48:63]
	ds_read_b64_tr_b16 v[108:109], v215 offset:0x2400
	ds_read_b64_tr_b16 v[110:111], v215 offset:0x2c00
	s_waitcnt lgkmcnt(6)
	v_mfma_f32_32x32x16_bf16 v[48:63], v[96:99], v[240:243], v[48:63]
	ds_read_b64_tr_b16 v[240:241], v215 offset:0x3400
	ds_read_b64_tr_b16 v[242:243], v215 offset:0x3c00
	s_waitcnt lgkmcnt(6)
	v_mfma_f32_32x32x16_bf16 v[32:47], v[232:235], v[100:103], v[32:47]
	ds_read_b64_tr_b16 v[100:101], v215 offset:0x600
	ds_read_b64_tr_b16 v[102:103], v215 offset:0xe00
	s_waitcnt lgkmcnt(6)
	v_mfma_f32_32x32x16_bf16 v[32:47], v[236:239], v[104:107], v[32:47]
	ds_read_b64_tr_b16 v[104:105], v215 offset:0x1600
	ds_read_b64_tr_b16 v[106:107], v215 offset:0x1e00
	s_waitcnt lgkmcnt(6)
	v_mfma_f32_32x32x16_bf16 v[32:47], v[228:231], v[108:111], v[32:47]
	ds_read_b64_tr_b16 v[108:109], v215 offset:0x2600
	ds_read_b64_tr_b16 v[110:111], v215 offset:0x2e00
	s_waitcnt lgkmcnt(6)
	v_mfma_f32_32x32x16_bf16 v[32:47], v[96:99], v[240:243], v[32:47]
	ds_read_b64_tr_b16 v[240:241], v215 offset:0x3600
	ds_read_b64_tr_b16 v[242:243], v215 offset:0x3e00
	s_waitcnt lgkmcnt(6)
	v_mfma_f32_32x32x16_bf16 v[16:31], v[232:235], v[100:103], v[16:31]
	s_lshl_b32 s16, s59, 14
	v_add_u32_e32 v100, s16, v218
	s_mul_i32 s11, s59, 0x2400
	s_waitcnt vmcnt(5)
	ds_write_b128 v100, v[162:165]
	s_waitcnt vmcnt(4)
	ds_write_b128 v100, v[166:169] offset:8192
	v_add_u32_e32 v100, s11, v219
	v_cmp_gt_f32_e32 vcc, 1.0, v226
	s_waitcnt lgkmcnt(6)
	v_mfma_f32_32x32x16_bf16 v[16:31], v[236:239], v[104:107], v[16:31]
	s_waitcnt vmcnt(3)
	ds_write_b128 v100, v[170:173] offset:49152
	s_waitcnt lgkmcnt(5)
	v_mfma_f32_32x32x16_bf16 v[16:31], v[228:231], v[108:111], v[16:31]
	s_waitcnt lgkmcnt(3)
	v_mfma_f32_32x32x16_bf16 v[16:31], v[96:99], v[240:243], v[16:31]
	s_cbranch_vccz .LBB0_1292
	s_and_saveexec_b64 s[8:9], s[6:7]
	ds_write_b32 v199, v226 offset:128
	s_or_b64 exec, exec, s[8:9]
	s_waitcnt lgkmcnt(0)
	v_add_u32_e32 v108, v191, v198
	ds_read_b128 v[96:99], v108 offset:224
	ds_read_b128 v[100:103], v108 offset:192
	ds_read_b128 v[104:107], v108 offset:160
	ds_read_b128 v[108:111], v108 offset:128
	s_waitcnt lgkmcnt(3)
	v_pk_mul_f32 v[12:13], v[12:13], v[96:97]
	s_waitcnt lgkmcnt(2)
	v_pk_mul_f32 v[8:9], v[8:9], v[100:101]
	s_waitcnt lgkmcnt(1)
	v_pk_mul_f32 v[4:5], v[4:5], v[104:105]
	v_pk_mul_f32 v[14:15], v[14:15], v[98:99]
	v_pk_mul_f32 v[10:11], v[10:11], v[102:103]
	v_pk_mul_f32 v[6:7], v[6:7], v[106:107]
	s_waitcnt lgkmcnt(0)
	v_pk_mul_f32 v[2:3], v[2:3], v[110:111]
	v_pk_mul_f32 v[0:1], v[0:1], v[108:109]
	v_pk_mul_f32 v[60:61], v[60:61], v[96:97]
	v_pk_mul_f32 v[56:57], v[56:57], v[100:101]
	v_pk_mul_f32 v[52:53], v[52:53], v[104:105]
	v_pk_mul_f32 v[62:63], v[62:63], v[98:99]
	v_pk_mul_f32 v[58:59], v[58:59], v[102:103]
	v_pk_mul_f32 v[54:55], v[54:55], v[106:107]
	v_pk_mul_f32 v[50:51], v[50:51], v[110:111]
	v_pk_mul_f32 v[48:49], v[48:49], v[108:109]
	v_pk_mul_f32 v[44:45], v[44:45], v[96:97]
	v_pk_mul_f32 v[40:41], v[40:41], v[100:101]
	v_pk_mul_f32 v[36:37], v[36:37], v[104:105]
	v_pk_mul_f32 v[46:47], v[46:47], v[98:99]
	v_pk_mul_f32 v[42:43], v[42:43], v[102:103]
	v_pk_mul_f32 v[38:39], v[38:39], v[106:107]
	v_pk_mul_f32 v[34:35], v[34:35], v[110:111]
	v_pk_mul_f32 v[32:33], v[32:33], v[108:109]
	v_pk_mul_f32 v[28:29], v[28:29], v[96:97]
	v_pk_mul_f32 v[24:25], v[24:25], v[100:101]
	v_pk_mul_f32 v[20:21], v[20:21], v[104:105]
	v_pk_mul_f32 v[30:31], v[30:31], v[98:99]
	v_pk_mul_f32 v[26:27], v[26:27], v[102:103]
	v_pk_mul_f32 v[22:23], v[22:23], v[106:107]
	v_pk_mul_f32 v[18:19], v[18:19], v[110:111]
	v_pk_mul_f32 v[16:17], v[16:17], v[108:109]
